# P9 sample-row small-tile GEMM: fragment loads streamed through a 19-quad VGPR ring with counted waits (was one load per wait)
# speedup vs baseline: 1.0326x; 1.0031x over previous
.LBB0_1252:
	s_lshl_b32 s10, s16, 2
	s_andn2_b32 s10, s10, 63
	s_addk_i32 s10, 0x4000
	s_lshl_b32 s11, s16, 6
	v_add_u32_e32 v4, s10, v129
	s_and_b32 s18, s11, 0x3c0
	v_ashrrev_i32_e32 v5, 31, v4
	v_or_b32_e32 v2, s18, v130
	v_lshlrev_b64 v[0:1], 11, v[4:5]
	v_lshl_add_u64 v[0:1], s[36:37], 0, v[0:1]
	v_lshlrev_b32_e32 v194, 1, v2
	v_lshlrev_b64 v[92:93], 6, v[4:5]
	v_lshl_add_u64 v[94:95], v[0:1], 0, v[194:195]
	v_lshl_add_u64 v[16:17], s[70:71], 0, v[92:93]
	global_load_dwordx4 v[0:3], v[94:95], off
	global_load_dwordx4 v[4:7], v[16:17], off offset:48
	global_load_dwordx4 v[8:11], v[16:17], off offset:32
	global_load_dwordx4 v[12:15], v[16:17], off offset:16
	s_nop 0
	global_load_dwordx4 v[16:19], v[16:17], off
	s_andn2_b64 vcc, exec, s[6:7]
	s_cbranch_vccnz .LBB0_1255
	s_and_b32 s10, s15, 0x3c0
	v_or_b32_e32 v20, s10, v128
	v_lshlrev_b32_e32 v21, 1, v20
	v_or_b32_e32 v22, 32, v21
	v_mad_i64_i32 v[96:97], s[10:11], s4, v22, v[86:87]
	v_or_b32_e32 v22, 0x60, v21
	v_or_b32_e32 v21, 64, v21
	v_mad_i64_i32 v[98:99], s[10:11], s4, v22, v[88:89]
	v_mad_i64_i32 v[100:101], s[10:11], s4, v21, v[88:89]
	v_mad_u64_u32 v[102:103], s[10:11], s8, v20, v[88:89]
	s_and_b32 s10, s14, 0xffffffc0
	v_mad_i32_i24 v103, s9, v20, v103
	v_add_u32_e32 v20, s10, v141
	v_ashrrev_i32_e32 v21, 31, v20
	v_mul_lo_u32 v22, s8, v21
	v_mul_lo_u32 v23, s9, v20
	v_mad_u64_u32 v[104:105], s[10:11], s8, v20, v[90:91]
	v_lshlrev_b64 v[20:21], 1, v[20:21]
	v_add3_u32 v105, v23, v105, v22
	v_lshl_add_u64 v[22:23], v[20:21], 0, s[42:43]
	v_mul_lo_u32 v23, s4, v23
	v_mul_lo_u32 v24, s5, v22
	v_mad_u64_u32 v[106:107], s[10:11], s4, v22, v[90:91]
	v_add3_u32 v107, v24, v107, v23
	v_lshl_add_u64 v[22:23], v[20:21], 0, 32
	v_lshl_add_u64 v[20:21], v[20:21], 0, 64
	v_mul_lo_u32 v23, s4, v23
	v_mul_lo_u32 v24, s5, v22
	v_mad_u64_u32 v[108:109], s[10:11], s4, v22, v[90:91]
	v_mul_lo_u32 v21, s4, v21
	v_mul_lo_u32 v22, s5, v20
	v_mad_u64_u32 v[110:111], s[10:11], s4, v20, v[90:91]
	v_mov_b32_e32 v28, 0
	v_add3_u32 v109, v24, v109, v23
	v_add3_u32 v111, v22, v111, v21
	s_mov_b32 s10, 0
	v_mov_b32_e32 v29, v28
	v_mov_b32_e32 v30, v28
	v_mov_b32_e32 v31, v28
	v_mov_b32_e32 v52, v28
	v_mov_b32_e32 v53, v28
	v_mov_b32_e32 v54, v28
	v_mov_b32_e32 v55, v28
	v_mov_b32_e32 v56, v28
	v_mov_b32_e32 v57, v28
	v_mov_b32_e32 v58, v28
	v_mov_b32_e32 v59, v28
	v_mov_b32_e32 v60, v28
	v_mov_b32_e32 v61, v28
	v_mov_b32_e32 v62, v28
	v_mov_b32_e32 v63, v28
	v_mov_b32_e32 v64, v28
	v_mov_b32_e32 v65, v28
	v_mov_b32_e32 v66, v28
	v_mov_b32_e32 v67, v28
	v_mov_b32_e32 v44, v28
	v_mov_b32_e32 v45, v28
	v_mov_b32_e32 v46, v28
	v_mov_b32_e32 v47, v28
	v_mov_b32_e32 v36, v28
	v_mov_b32_e32 v37, v28
	v_mov_b32_e32 v38, v28
	v_mov_b32_e32 v39, v28
	v_mov_b32_e32 v24, v28
	v_mov_b32_e32 v25, v28
	v_mov_b32_e32 v26, v28
	v_mov_b32_e32 v27, v28
	v_mov_b32_e32 v48, v28
	v_mov_b32_e32 v49, v28
	v_mov_b32_e32 v50, v28
	v_mov_b32_e32 v51, v28
	v_mov_b32_e32 v40, v28
	v_mov_b32_e32 v41, v28
	v_mov_b32_e32 v42, v28
	v_mov_b32_e32 v43, v28
	v_mov_b32_e32 v32, v28
	v_mov_b32_e32 v33, v28
	v_mov_b32_e32 v34, v28
	v_mov_b32_e32 v35, v28
	v_mov_b32_e32 v20, v28
	v_mov_b32_e32 v21, v28
	v_mov_b32_e32 v22, v28
	v_mov_b32_e32 v23, v28
	v_mov_b32_e32 v76, v28
	v_mov_b32_e32 v77, v28
	v_mov_b32_e32 v78, v28
	v_mov_b32_e32 v79, v28
	v_mov_b32_e32 v72, v28
	v_mov_b32_e32 v73, v28
	v_mov_b32_e32 v74, v28
	v_mov_b32_e32 v75, v28
	v_mov_b32_e32 v80, v28
	v_mov_b32_e32 v81, v28
	v_mov_b32_e32 v82, v28
	v_mov_b32_e32 v83, v28
	v_mov_b32_e32 v68, v28
	v_mov_b32_e32 v69, v28
	v_mov_b32_e32 v70, v28
	v_mov_b32_e32 v71, v28
	s_cmpk_lg_i32 s3, 0x200
	s_cbranch_scc1 .LBB0_1254
	v_lshl_add_u64 v[126:127], v[102:103], 0, v[84:85]
	v_lshl_add_u64 v[124:125], v[96:97], 0, v[84:85]
	v_lshl_add_u64 v[120:121], v[100:101], 0, v[84:85]
	v_lshl_add_u64 v[118:119], v[98:99], 0, v[84:85]
	v_lshl_add_u64 v[122:123], v[104:105], 0, v[84:85]
	v_lshl_add_u64 v[114:115], v[108:109], 0, v[84:85]
	v_lshl_add_u64 v[116:117], v[110:111], 0, v[84:85]
	v_lshl_add_u64 v[112:113], v[106:107], 0, v[84:85]
	global_load_dwordx4 v[146:149], v[126:127], off
	global_load_dwordx4 v[150:153], v[124:125], off offset:-128
	global_load_dwordx4 v[154:157], v[120:121], off
	global_load_dwordx4 v[158:161], v[118:119], off
	global_load_dwordx4 v[162:165], v[122:123], off offset:-128
	global_load_dwordx4 v[166:169], v[114:115], off offset:-128
	global_load_dwordx4 v[170:173], v[116:117], off offset:-128
	global_load_dwordx4 v[174:177], v[112:113], off offset:-128
	global_load_dwordx4 v[178:181], v[126:127], off offset:16
	global_load_dwordx4 v[182:185], v[124:125], off offset:-112
	global_load_dwordx4 v[186:189], v[120:121], off offset:16
	global_load_dwordx4 v[198:201], v[118:119], off offset:16
	global_load_dwordx4 v[218:221], v[122:123], off offset:-112
	global_load_dwordx4 v[222:225], v[114:115], off offset:-112
	global_load_dwordx4 v[226:229], v[116:117], off offset:-112
	global_load_dwordx4 v[230:233], v[112:113], off offset:-112
	global_load_dwordx4 v[234:237], v[126:127], off offset:128
	global_load_dwordx4 v[238:241], v[124:125], off
	global_load_dwordx4 v[246:249], v[120:121], off offset:128
	s_waitcnt vmcnt(14)
	v_mfma_f32_16x16x32_bf16 v[28:31], v[146:149], v[162:165], v[28:31]
	s_waitcnt vmcnt(14)
	v_mfma_f32_16x16x32_bf16 v[52:55], v[150:153], v[162:165], v[52:55]
	s_waitcnt vmcnt(14)
	v_mfma_f32_16x16x32_bf16 v[56:59], v[154:157], v[162:165], v[56:59]
	s_waitcnt vmcnt(14)
	v_mfma_f32_16x16x32_bf16 v[60:63], v[158:161], v[162:165], v[60:63]
	global_load_dwordx4 v[162:165], v[118:119], off offset:128
	s_waitcnt vmcnt(14)
	v_mfma_f32_16x16x32_bf16 v[64:67], v[146:149], v[166:169], v[64:67]
	v_mfma_f32_16x16x32_bf16 v[44:47], v[150:153], v[166:169], v[44:47]
	v_mfma_f32_16x16x32_bf16 v[36:39], v[154:157], v[166:169], v[36:39]
	v_mfma_f32_16x16x32_bf16 v[24:27], v[158:161], v[166:169], v[24:27]
	global_load_dwordx4 v[166:169], v[122:123], off
	s_waitcnt vmcnt(14)
	v_mfma_f32_16x16x32_bf16 v[48:51], v[146:149], v[170:173], v[48:51]
	v_mfma_f32_16x16x32_bf16 v[40:43], v[150:153], v[170:173], v[40:43]
	v_mfma_f32_16x16x32_bf16 v[32:35], v[154:157], v[170:173], v[32:35]
	v_mfma_f32_16x16x32_bf16 v[20:23], v[158:161], v[170:173], v[20:23]
	global_load_dwordx4 v[170:173], v[114:115], off
	s_waitcnt vmcnt(14)
	v_mfma_f32_16x16x32_bf16 v[76:79], v[146:149], v[174:177], v[76:79]
	global_load_dwordx4 v[146:149], v[116:117], off
	v_mfma_f32_16x16x32_bf16 v[72:75], v[150:153], v[174:177], v[72:75]
	global_load_dwordx4 v[150:153], v[112:113], off
	v_mfma_f32_16x16x32_bf16 v[80:83], v[154:157], v[174:177], v[80:83]
	global_load_dwordx4 v[154:157], v[126:127], off offset:144
	v_mfma_f32_16x16x32_bf16 v[68:71], v[158:161], v[174:177], v[68:71]
	global_load_dwordx4 v[158:161], v[124:125], off offset:16
	global_load_dwordx4 v[174:177], v[120:121], off offset:144
	s_waitcnt vmcnt(14)
	v_mfma_f32_16x16x32_bf16 v[28:31], v[178:181], v[218:221], v[28:31]
	s_waitcnt vmcnt(14)
	v_mfma_f32_16x16x32_bf16 v[52:55], v[182:185], v[218:221], v[52:55]
	s_waitcnt vmcnt(14)
	v_mfma_f32_16x16x32_bf16 v[56:59], v[186:189], v[218:221], v[56:59]
	s_waitcnt vmcnt(14)
	v_mfma_f32_16x16x32_bf16 v[60:63], v[198:201], v[218:221], v[60:63]
	global_load_dwordx4 v[218:221], v[118:119], off offset:144
	s_waitcnt vmcnt(14)
	v_mfma_f32_16x16x32_bf16 v[64:67], v[178:181], v[222:225], v[64:67]
	v_mfma_f32_16x16x32_bf16 v[44:47], v[182:185], v[222:225], v[44:47]
	v_mfma_f32_16x16x32_bf16 v[36:39], v[186:189], v[222:225], v[36:39]
	v_mfma_f32_16x16x32_bf16 v[24:27], v[198:201], v[222:225], v[24:27]
	global_load_dwordx4 v[222:225], v[122:123], off offset:16
	s_waitcnt vmcnt(14)
	v_mfma_f32_16x16x32_bf16 v[48:51], v[178:181], v[226:229], v[48:51]
	v_mfma_f32_16x16x32_bf16 v[40:43], v[182:185], v[226:229], v[40:43]
	v_mfma_f32_16x16x32_bf16 v[32:35], v[186:189], v[226:229], v[32:35]
	v_mfma_f32_16x16x32_bf16 v[20:23], v[198:201], v[226:229], v[20:23]
	global_load_dwordx4 v[226:229], v[114:115], off offset:16
	s_waitcnt vmcnt(14)
	v_mfma_f32_16x16x32_bf16 v[76:79], v[178:181], v[230:233], v[76:79]
	global_load_dwordx4 v[178:181], v[116:117], off offset:16
	v_mfma_f32_16x16x32_bf16 v[72:75], v[182:185], v[230:233], v[72:75]
	global_load_dwordx4 v[182:185], v[112:113], off offset:16
	v_mfma_f32_16x16x32_bf16 v[80:83], v[186:189], v[230:233], v[80:83]
	global_load_dwordx4 v[186:189], v[126:127], off offset:256
	v_mfma_f32_16x16x32_bf16 v[68:71], v[198:201], v[230:233], v[68:71]
	global_load_dwordx4 v[198:201], v[124:125], off offset:128
	global_load_dwordx4 v[230:233], v[120:121], off offset:256
	s_waitcnt vmcnt(14)
	v_mfma_f32_16x16x32_bf16 v[28:31], v[234:237], v[166:169], v[28:31]
	s_waitcnt vmcnt(14)
	v_mfma_f32_16x16x32_bf16 v[52:55], v[238:241], v[166:169], v[52:55]
	s_waitcnt vmcnt(14)
	v_mfma_f32_16x16x32_bf16 v[56:59], v[246:249], v[166:169], v[56:59]
	s_waitcnt vmcnt(14)
	v_mfma_f32_16x16x32_bf16 v[60:63], v[162:165], v[166:169], v[60:63]
	global_load_dwordx4 v[166:169], v[118:119], off offset:256
	s_waitcnt vmcnt(14)
	v_mfma_f32_16x16x32_bf16 v[64:67], v[234:237], v[170:173], v[64:67]
	v_mfma_f32_16x16x32_bf16 v[44:47], v[238:241], v[170:173], v[44:47]
	v_mfma_f32_16x16x32_bf16 v[36:39], v[246:249], v[170:173], v[36:39]
	v_mfma_f32_16x16x32_bf16 v[24:27], v[162:165], v[170:173], v[24:27]
	global_load_dwordx4 v[170:173], v[122:123], off offset:128
	s_waitcnt vmcnt(14)
	v_mfma_f32_16x16x32_bf16 v[48:51], v[234:237], v[146:149], v[48:51]
	v_mfma_f32_16x16x32_bf16 v[40:43], v[238:241], v[146:149], v[40:43]
	v_mfma_f32_16x16x32_bf16 v[32:35], v[246:249], v[146:149], v[32:35]
	v_mfma_f32_16x16x32_bf16 v[20:23], v[162:165], v[146:149], v[20:23]
	global_load_dwordx4 v[146:149], v[114:115], off offset:128
	s_waitcnt vmcnt(14)
	v_mfma_f32_16x16x32_bf16 v[76:79], v[234:237], v[150:153], v[76:79]
	global_load_dwordx4 v[234:237], v[116:117], off offset:128
	v_mfma_f32_16x16x32_bf16 v[72:75], v[238:241], v[150:153], v[72:75]
	global_load_dwordx4 v[238:241], v[112:113], off offset:128
	v_mfma_f32_16x16x32_bf16 v[80:83], v[246:249], v[150:153], v[80:83]
	global_load_dwordx4 v[246:249], v[126:127], off offset:272
	v_mfma_f32_16x16x32_bf16 v[68:71], v[162:165], v[150:153], v[68:71]
	global_load_dwordx4 v[162:165], v[124:125], off offset:144
	global_load_dwordx4 v[150:153], v[120:121], off offset:272
	s_waitcnt vmcnt(14)
	v_mfma_f32_16x16x32_bf16 v[28:31], v[154:157], v[222:225], v[28:31]
	s_waitcnt vmcnt(14)
	v_mfma_f32_16x16x32_bf16 v[52:55], v[158:161], v[222:225], v[52:55]
	s_waitcnt vmcnt(14)
	v_mfma_f32_16x16x32_bf16 v[56:59], v[174:177], v[222:225], v[56:59]
	s_waitcnt vmcnt(14)
	v_mfma_f32_16x16x32_bf16 v[60:63], v[218:221], v[222:225], v[60:63]
	global_load_dwordx4 v[222:225], v[118:119], off offset:272
	s_waitcnt vmcnt(14)
	v_mfma_f32_16x16x32_bf16 v[64:67], v[154:157], v[226:229], v[64:67]
	v_mfma_f32_16x16x32_bf16 v[44:47], v[158:161], v[226:229], v[44:47]
	v_mfma_f32_16x16x32_bf16 v[36:39], v[174:177], v[226:229], v[36:39]
	v_mfma_f32_16x16x32_bf16 v[24:27], v[218:221], v[226:229], v[24:27]
	global_load_dwordx4 v[226:229], v[122:123], off offset:144
	s_waitcnt vmcnt(14)
	v_mfma_f32_16x16x32_bf16 v[48:51], v[154:157], v[178:181], v[48:51]
	v_mfma_f32_16x16x32_bf16 v[40:43], v[158:161], v[178:181], v[40:43]
	v_mfma_f32_16x16x32_bf16 v[32:35], v[174:177], v[178:181], v[32:35]
	v_mfma_f32_16x16x32_bf16 v[20:23], v[218:221], v[178:181], v[20:23]
	global_load_dwordx4 v[178:181], v[114:115], off offset:144
	s_waitcnt vmcnt(14)
	v_mfma_f32_16x16x32_bf16 v[76:79], v[154:157], v[182:185], v[76:79]
	global_load_dwordx4 v[154:157], v[116:117], off offset:144
	v_mfma_f32_16x16x32_bf16 v[72:75], v[158:161], v[182:185], v[72:75]
	global_load_dwordx4 v[158:161], v[112:113], off offset:144
	v_mfma_f32_16x16x32_bf16 v[80:83], v[174:177], v[182:185], v[80:83]
	global_load_dwordx4 v[174:177], v[126:127], off offset:384
	v_mfma_f32_16x16x32_bf16 v[68:71], v[218:221], v[182:185], v[68:71]
	global_load_dwordx4 v[218:221], v[124:125], off offset:256
	global_load_dwordx4 v[182:185], v[120:121], off offset:384
	s_waitcnt vmcnt(14)
	v_mfma_f32_16x16x32_bf16 v[28:31], v[186:189], v[170:173], v[28:31]
	s_waitcnt vmcnt(14)
	v_mfma_f32_16x16x32_bf16 v[52:55], v[198:201], v[170:173], v[52:55]
	s_waitcnt vmcnt(14)
	v_mfma_f32_16x16x32_bf16 v[56:59], v[230:233], v[170:173], v[56:59]
	s_waitcnt vmcnt(14)
	v_mfma_f32_16x16x32_bf16 v[60:63], v[166:169], v[170:173], v[60:63]
	global_load_dwordx4 v[170:173], v[118:119], off offset:384
	s_waitcnt vmcnt(14)
	v_mfma_f32_16x16x32_bf16 v[64:67], v[186:189], v[146:149], v[64:67]
	v_mfma_f32_16x16x32_bf16 v[44:47], v[198:201], v[146:149], v[44:47]
	v_mfma_f32_16x16x32_bf16 v[36:39], v[230:233], v[146:149], v[36:39]
	v_mfma_f32_16x16x32_bf16 v[24:27], v[166:169], v[146:149], v[24:27]
	global_load_dwordx4 v[146:149], v[122:123], off offset:256
	s_waitcnt vmcnt(14)
	v_mfma_f32_16x16x32_bf16 v[48:51], v[186:189], v[234:237], v[48:51]
	v_mfma_f32_16x16x32_bf16 v[40:43], v[198:201], v[234:237], v[40:43]
	v_mfma_f32_16x16x32_bf16 v[32:35], v[230:233], v[234:237], v[32:35]
	v_mfma_f32_16x16x32_bf16 v[20:23], v[166:169], v[234:237], v[20:23]
	global_load_dwordx4 v[234:237], v[114:115], off offset:256
	s_waitcnt vmcnt(14)
	v_mfma_f32_16x16x32_bf16 v[76:79], v[186:189], v[238:241], v[76:79]
	global_load_dwordx4 v[186:189], v[116:117], off offset:256
	v_mfma_f32_16x16x32_bf16 v[72:75], v[198:201], v[238:241], v[72:75]
	global_load_dwordx4 v[198:201], v[112:113], off offset:256
	v_mfma_f32_16x16x32_bf16 v[80:83], v[230:233], v[238:241], v[80:83]
	global_load_dwordx4 v[230:233], v[126:127], off offset:400
	v_mfma_f32_16x16x32_bf16 v[68:71], v[166:169], v[238:241], v[68:71]
	global_load_dwordx4 v[166:169], v[124:125], off offset:272
	global_load_dwordx4 v[238:241], v[120:121], off offset:400
	s_waitcnt vmcnt(14)
	v_mfma_f32_16x16x32_bf16 v[28:31], v[246:249], v[226:229], v[28:31]
	s_waitcnt vmcnt(14)
	v_mfma_f32_16x16x32_bf16 v[52:55], v[162:165], v[226:229], v[52:55]
	s_waitcnt vmcnt(14)
	v_mfma_f32_16x16x32_bf16 v[56:59], v[150:153], v[226:229], v[56:59]
	s_waitcnt vmcnt(14)
	v_mfma_f32_16x16x32_bf16 v[60:63], v[222:225], v[226:229], v[60:63]
	global_load_dwordx4 v[226:229], v[118:119], off offset:400
	s_waitcnt vmcnt(14)
	v_mfma_f32_16x16x32_bf16 v[64:67], v[246:249], v[178:181], v[64:67]
	v_mfma_f32_16x16x32_bf16 v[44:47], v[162:165], v[178:181], v[44:47]
	v_mfma_f32_16x16x32_bf16 v[36:39], v[150:153], v[178:181], v[36:39]
	v_mfma_f32_16x16x32_bf16 v[24:27], v[222:225], v[178:181], v[24:27]
	global_load_dwordx4 v[178:181], v[122:123], off offset:272
	s_waitcnt vmcnt(14)
	v_mfma_f32_16x16x32_bf16 v[48:51], v[246:249], v[154:157], v[48:51]
	v_mfma_f32_16x16x32_bf16 v[40:43], v[162:165], v[154:157], v[40:43]
	v_mfma_f32_16x16x32_bf16 v[32:35], v[150:153], v[154:157], v[32:35]
	v_mfma_f32_16x16x32_bf16 v[20:23], v[222:225], v[154:157], v[20:23]
	global_load_dwordx4 v[154:157], v[114:115], off offset:272
	s_waitcnt vmcnt(14)
	v_mfma_f32_16x16x32_bf16 v[76:79], v[246:249], v[158:161], v[76:79]
	global_load_dwordx4 v[246:249], v[116:117], off offset:272
	v_mfma_f32_16x16x32_bf16 v[72:75], v[162:165], v[158:161], v[72:75]
	global_load_dwordx4 v[162:165], v[112:113], off offset:272
	v_mfma_f32_16x16x32_bf16 v[80:83], v[150:153], v[158:161], v[80:83]
	global_load_dwordx4 v[150:153], v[126:127], off offset:512
	v_mfma_f32_16x16x32_bf16 v[68:71], v[222:225], v[158:161], v[68:71]
	global_load_dwordx4 v[222:225], v[124:125], off offset:384
	global_load_dwordx4 v[158:161], v[120:121], off offset:512
	s_waitcnt vmcnt(14)
	v_mfma_f32_16x16x32_bf16 v[28:31], v[174:177], v[146:149], v[28:31]
	s_waitcnt vmcnt(14)
	v_mfma_f32_16x16x32_bf16 v[52:55], v[218:221], v[146:149], v[52:55]
	s_waitcnt vmcnt(14)
	v_mfma_f32_16x16x32_bf16 v[56:59], v[182:185], v[146:149], v[56:59]
	s_waitcnt vmcnt(14)
	v_mfma_f32_16x16x32_bf16 v[60:63], v[170:173], v[146:149], v[60:63]
	global_load_dwordx4 v[146:149], v[118:119], off offset:512
	s_waitcnt vmcnt(14)
	v_mfma_f32_16x16x32_bf16 v[64:67], v[174:177], v[234:237], v[64:67]
	v_mfma_f32_16x16x32_bf16 v[44:47], v[218:221], v[234:237], v[44:47]
	v_mfma_f32_16x16x32_bf16 v[36:39], v[182:185], v[234:237], v[36:39]
	v_mfma_f32_16x16x32_bf16 v[24:27], v[170:173], v[234:237], v[24:27]
	global_load_dwordx4 v[234:237], v[122:123], off offset:384
	s_waitcnt vmcnt(14)
	v_mfma_f32_16x16x32_bf16 v[48:51], v[174:177], v[186:189], v[48:51]
	v_mfma_f32_16x16x32_bf16 v[40:43], v[218:221], v[186:189], v[40:43]
	v_mfma_f32_16x16x32_bf16 v[32:35], v[182:185], v[186:189], v[32:35]
	v_mfma_f32_16x16x32_bf16 v[20:23], v[170:173], v[186:189], v[20:23]
	global_load_dwordx4 v[186:189], v[114:115], off offset:384
	s_waitcnt vmcnt(14)
	v_mfma_f32_16x16x32_bf16 v[76:79], v[174:177], v[198:201], v[76:79]
	global_load_dwordx4 v[174:177], v[116:117], off offset:384
	v_mfma_f32_16x16x32_bf16 v[72:75], v[218:221], v[198:201], v[72:75]
	global_load_dwordx4 v[218:221], v[112:113], off offset:384
	v_mfma_f32_16x16x32_bf16 v[80:83], v[182:185], v[198:201], v[80:83]
	global_load_dwordx4 v[182:185], v[126:127], off offset:528
	v_mfma_f32_16x16x32_bf16 v[68:71], v[170:173], v[198:201], v[68:71]
	global_load_dwordx4 v[170:173], v[124:125], off offset:400
	global_load_dwordx4 v[198:201], v[120:121], off offset:528
	s_waitcnt vmcnt(14)
	v_mfma_f32_16x16x32_bf16 v[28:31], v[230:233], v[178:181], v[28:31]
	s_waitcnt vmcnt(14)
	v_mfma_f32_16x16x32_bf16 v[52:55], v[166:169], v[178:181], v[52:55]
	s_waitcnt vmcnt(14)
	v_mfma_f32_16x16x32_bf16 v[56:59], v[238:241], v[178:181], v[56:59]
	s_waitcnt vmcnt(14)
	v_mfma_f32_16x16x32_bf16 v[60:63], v[226:229], v[178:181], v[60:63]
	global_load_dwordx4 v[178:181], v[118:119], off offset:528
	s_waitcnt vmcnt(14)
	v_mfma_f32_16x16x32_bf16 v[64:67], v[230:233], v[154:157], v[64:67]
	v_mfma_f32_16x16x32_bf16 v[44:47], v[166:169], v[154:157], v[44:47]
	v_mfma_f32_16x16x32_bf16 v[36:39], v[238:241], v[154:157], v[36:39]
	v_mfma_f32_16x16x32_bf16 v[24:27], v[226:229], v[154:157], v[24:27]
	global_load_dwordx4 v[154:157], v[122:123], off offset:400
	s_waitcnt vmcnt(14)
	v_mfma_f32_16x16x32_bf16 v[48:51], v[230:233], v[246:249], v[48:51]
	v_mfma_f32_16x16x32_bf16 v[40:43], v[166:169], v[246:249], v[40:43]
	v_mfma_f32_16x16x32_bf16 v[32:35], v[238:241], v[246:249], v[32:35]
	v_mfma_f32_16x16x32_bf16 v[20:23], v[226:229], v[246:249], v[20:23]
	global_load_dwordx4 v[246:249], v[114:115], off offset:400
	s_waitcnt vmcnt(14)
	v_mfma_f32_16x16x32_bf16 v[76:79], v[230:233], v[162:165], v[76:79]
	global_load_dwordx4 v[230:233], v[116:117], off offset:400
	v_mfma_f32_16x16x32_bf16 v[72:75], v[166:169], v[162:165], v[72:75]
	global_load_dwordx4 v[166:169], v[112:113], off offset:400
	v_mfma_f32_16x16x32_bf16 v[80:83], v[238:241], v[162:165], v[80:83]
	global_load_dwordx4 v[238:241], v[126:127], off offset:640
	v_mfma_f32_16x16x32_bf16 v[68:71], v[226:229], v[162:165], v[68:71]
	global_load_dwordx4 v[226:229], v[124:125], off offset:512
	global_load_dwordx4 v[162:165], v[120:121], off offset:640
	s_waitcnt vmcnt(14)
	v_mfma_f32_16x16x32_bf16 v[28:31], v[150:153], v[234:237], v[28:31]
	s_waitcnt vmcnt(14)
	v_mfma_f32_16x16x32_bf16 v[52:55], v[222:225], v[234:237], v[52:55]
	s_waitcnt vmcnt(14)
	v_mfma_f32_16x16x32_bf16 v[56:59], v[158:161], v[234:237], v[56:59]
	s_waitcnt vmcnt(14)
	v_mfma_f32_16x16x32_bf16 v[60:63], v[146:149], v[234:237], v[60:63]
	global_load_dwordx4 v[234:237], v[118:119], off offset:640
	s_waitcnt vmcnt(14)
	v_mfma_f32_16x16x32_bf16 v[64:67], v[150:153], v[186:189], v[64:67]
	v_mfma_f32_16x16x32_bf16 v[44:47], v[222:225], v[186:189], v[44:47]
	v_mfma_f32_16x16x32_bf16 v[36:39], v[158:161], v[186:189], v[36:39]
	v_mfma_f32_16x16x32_bf16 v[24:27], v[146:149], v[186:189], v[24:27]
	global_load_dwordx4 v[186:189], v[122:123], off offset:512
	s_waitcnt vmcnt(14)
	v_mfma_f32_16x16x32_bf16 v[48:51], v[150:153], v[174:177], v[48:51]
	v_mfma_f32_16x16x32_bf16 v[40:43], v[222:225], v[174:177], v[40:43]
	v_mfma_f32_16x16x32_bf16 v[32:35], v[158:161], v[174:177], v[32:35]
	v_mfma_f32_16x16x32_bf16 v[20:23], v[146:149], v[174:177], v[20:23]
	global_load_dwordx4 v[174:177], v[114:115], off offset:512
	s_waitcnt vmcnt(14)
	v_mfma_f32_16x16x32_bf16 v[76:79], v[150:153], v[218:221], v[76:79]
	global_load_dwordx4 v[150:153], v[116:117], off offset:512
	v_mfma_f32_16x16x32_bf16 v[72:75], v[222:225], v[218:221], v[72:75]
	global_load_dwordx4 v[222:225], v[112:113], off offset:512
	v_mfma_f32_16x16x32_bf16 v[80:83], v[158:161], v[218:221], v[80:83]
	global_load_dwordx4 v[158:161], v[126:127], off offset:656
	v_mfma_f32_16x16x32_bf16 v[68:71], v[146:149], v[218:221], v[68:71]
	global_load_dwordx4 v[146:149], v[124:125], off offset:528
	global_load_dwordx4 v[218:221], v[120:121], off offset:656
	s_waitcnt vmcnt(14)
	v_mfma_f32_16x16x32_bf16 v[28:31], v[182:185], v[154:157], v[28:31]
	s_waitcnt vmcnt(14)
	v_mfma_f32_16x16x32_bf16 v[52:55], v[170:173], v[154:157], v[52:55]
	s_waitcnt vmcnt(14)
	v_mfma_f32_16x16x32_bf16 v[56:59], v[198:201], v[154:157], v[56:59]
	s_waitcnt vmcnt(14)
	v_mfma_f32_16x16x32_bf16 v[60:63], v[178:181], v[154:157], v[60:63]
	global_load_dwordx4 v[154:157], v[118:119], off offset:656
	s_waitcnt vmcnt(14)
	v_mfma_f32_16x16x32_bf16 v[64:67], v[182:185], v[246:249], v[64:67]
	v_mfma_f32_16x16x32_bf16 v[44:47], v[170:173], v[246:249], v[44:47]
	v_mfma_f32_16x16x32_bf16 v[36:39], v[198:201], v[246:249], v[36:39]
	v_mfma_f32_16x16x32_bf16 v[24:27], v[178:181], v[246:249], v[24:27]
	global_load_dwordx4 v[246:249], v[122:123], off offset:528
	s_waitcnt vmcnt(14)
	v_mfma_f32_16x16x32_bf16 v[48:51], v[182:185], v[230:233], v[48:51]
	v_mfma_f32_16x16x32_bf16 v[40:43], v[170:173], v[230:233], v[40:43]
	v_mfma_f32_16x16x32_bf16 v[32:35], v[198:201], v[230:233], v[32:35]
	v_mfma_f32_16x16x32_bf16 v[20:23], v[178:181], v[230:233], v[20:23]
	global_load_dwordx4 v[230:233], v[114:115], off offset:528
	s_waitcnt vmcnt(14)
	v_mfma_f32_16x16x32_bf16 v[76:79], v[182:185], v[166:169], v[76:79]
	global_load_dwordx4 v[182:185], v[116:117], off offset:528
	v_mfma_f32_16x16x32_bf16 v[72:75], v[170:173], v[166:169], v[72:75]
	global_load_dwordx4 v[170:173], v[112:113], off offset:528
	v_mfma_f32_16x16x32_bf16 v[80:83], v[198:201], v[166:169], v[80:83]
	global_load_dwordx4 v[198:201], v[126:127], off offset:768
	v_mfma_f32_16x16x32_bf16 v[68:71], v[178:181], v[166:169], v[68:71]
	global_load_dwordx4 v[178:181], v[124:125], off offset:640
	global_load_dwordx4 v[166:169], v[120:121], off offset:768
	s_waitcnt vmcnt(14)
	v_mfma_f32_16x16x32_bf16 v[28:31], v[238:241], v[186:189], v[28:31]
	s_waitcnt vmcnt(14)
	v_mfma_f32_16x16x32_bf16 v[52:55], v[226:229], v[186:189], v[52:55]
	s_waitcnt vmcnt(14)
	v_mfma_f32_16x16x32_bf16 v[56:59], v[162:165], v[186:189], v[56:59]
	s_waitcnt vmcnt(14)
	v_mfma_f32_16x16x32_bf16 v[60:63], v[234:237], v[186:189], v[60:63]
	global_load_dwordx4 v[186:189], v[118:119], off offset:768
	s_waitcnt vmcnt(14)
	v_mfma_f32_16x16x32_bf16 v[64:67], v[238:241], v[174:177], v[64:67]
	v_mfma_f32_16x16x32_bf16 v[44:47], v[226:229], v[174:177], v[44:47]
	v_mfma_f32_16x16x32_bf16 v[36:39], v[162:165], v[174:177], v[36:39]
	v_mfma_f32_16x16x32_bf16 v[24:27], v[234:237], v[174:177], v[24:27]
	global_load_dwordx4 v[174:177], v[122:123], off offset:640
	s_waitcnt vmcnt(14)
	v_mfma_f32_16x16x32_bf16 v[48:51], v[238:241], v[150:153], v[48:51]
	v_mfma_f32_16x16x32_bf16 v[40:43], v[226:229], v[150:153], v[40:43]
	v_mfma_f32_16x16x32_bf16 v[32:35], v[162:165], v[150:153], v[32:35]
	v_mfma_f32_16x16x32_bf16 v[20:23], v[234:237], v[150:153], v[20:23]
	global_load_dwordx4 v[150:153], v[114:115], off offset:640
	s_waitcnt vmcnt(14)
	v_mfma_f32_16x16x32_bf16 v[76:79], v[238:241], v[222:225], v[76:79]
	global_load_dwordx4 v[238:241], v[116:117], off offset:640
	v_mfma_f32_16x16x32_bf16 v[72:75], v[226:229], v[222:225], v[72:75]
	global_load_dwordx4 v[226:229], v[112:113], off offset:640
	v_mfma_f32_16x16x32_bf16 v[80:83], v[162:165], v[222:225], v[80:83]
	global_load_dwordx4 v[162:165], v[126:127], off offset:784
	v_mfma_f32_16x16x32_bf16 v[68:71], v[234:237], v[222:225], v[68:71]
	global_load_dwordx4 v[234:237], v[124:125], off offset:656
	global_load_dwordx4 v[222:225], v[120:121], off offset:784
	s_waitcnt vmcnt(14)
	v_mfma_f32_16x16x32_bf16 v[28:31], v[158:161], v[246:249], v[28:31]
	s_waitcnt vmcnt(14)
	v_mfma_f32_16x16x32_bf16 v[52:55], v[146:149], v[246:249], v[52:55]
	s_waitcnt vmcnt(14)
	v_mfma_f32_16x16x32_bf16 v[56:59], v[218:221], v[246:249], v[56:59]
	s_waitcnt vmcnt(14)
	v_mfma_f32_16x16x32_bf16 v[60:63], v[154:157], v[246:249], v[60:63]
	global_load_dwordx4 v[246:249], v[118:119], off offset:784
	s_waitcnt vmcnt(14)
	v_mfma_f32_16x16x32_bf16 v[64:67], v[158:161], v[230:233], v[64:67]
	v_mfma_f32_16x16x32_bf16 v[44:47], v[146:149], v[230:233], v[44:47]
	v_mfma_f32_16x16x32_bf16 v[36:39], v[218:221], v[230:233], v[36:39]
	v_mfma_f32_16x16x32_bf16 v[24:27], v[154:157], v[230:233], v[24:27]
	global_load_dwordx4 v[230:233], v[122:123], off offset:656
	s_waitcnt vmcnt(14)
	v_mfma_f32_16x16x32_bf16 v[48:51], v[158:161], v[182:185], v[48:51]
	v_mfma_f32_16x16x32_bf16 v[40:43], v[146:149], v[182:185], v[40:43]
	v_mfma_f32_16x16x32_bf16 v[32:35], v[218:221], v[182:185], v[32:35]
	v_mfma_f32_16x16x32_bf16 v[20:23], v[154:157], v[182:185], v[20:23]
	global_load_dwordx4 v[182:185], v[114:115], off offset:656
	s_waitcnt vmcnt(14)
	v_mfma_f32_16x16x32_bf16 v[76:79], v[158:161], v[170:173], v[76:79]
	global_load_dwordx4 v[158:161], v[116:117], off offset:656
	v_mfma_f32_16x16x32_bf16 v[72:75], v[146:149], v[170:173], v[72:75]
	global_load_dwordx4 v[146:149], v[112:113], off offset:656
	v_mfma_f32_16x16x32_bf16 v[80:83], v[218:221], v[170:173], v[80:83]
	global_load_dwordx4 v[218:221], v[126:127], off offset:896
	v_mfma_f32_16x16x32_bf16 v[68:71], v[154:157], v[170:173], v[68:71]
	global_load_dwordx4 v[154:157], v[124:125], off offset:768
	global_load_dwordx4 v[170:173], v[120:121], off offset:896
	s_waitcnt vmcnt(14)
	v_mfma_f32_16x16x32_bf16 v[28:31], v[198:201], v[174:177], v[28:31]
	s_waitcnt vmcnt(14)
	v_mfma_f32_16x16x32_bf16 v[52:55], v[178:181], v[174:177], v[52:55]
	s_waitcnt vmcnt(14)
	v_mfma_f32_16x16x32_bf16 v[56:59], v[166:169], v[174:177], v[56:59]
	s_waitcnt vmcnt(14)
	v_mfma_f32_16x16x32_bf16 v[60:63], v[186:189], v[174:177], v[60:63]
	global_load_dwordx4 v[174:177], v[118:119], off offset:896
	s_waitcnt vmcnt(14)
	v_mfma_f32_16x16x32_bf16 v[64:67], v[198:201], v[150:153], v[64:67]
	v_mfma_f32_16x16x32_bf16 v[44:47], v[178:181], v[150:153], v[44:47]
	v_mfma_f32_16x16x32_bf16 v[36:39], v[166:169], v[150:153], v[36:39]
	v_mfma_f32_16x16x32_bf16 v[24:27], v[186:189], v[150:153], v[24:27]
	global_load_dwordx4 v[150:153], v[122:123], off offset:768
	s_waitcnt vmcnt(14)
	v_mfma_f32_16x16x32_bf16 v[48:51], v[198:201], v[238:241], v[48:51]
	v_mfma_f32_16x16x32_bf16 v[40:43], v[178:181], v[238:241], v[40:43]
	v_mfma_f32_16x16x32_bf16 v[32:35], v[166:169], v[238:241], v[32:35]
	v_mfma_f32_16x16x32_bf16 v[20:23], v[186:189], v[238:241], v[20:23]
	global_load_dwordx4 v[238:241], v[114:115], off offset:768
	s_waitcnt vmcnt(14)
	v_mfma_f32_16x16x32_bf16 v[76:79], v[198:201], v[226:229], v[76:79]
	global_load_dwordx4 v[198:201], v[116:117], off offset:768
	v_mfma_f32_16x16x32_bf16 v[72:75], v[178:181], v[226:229], v[72:75]
	global_load_dwordx4 v[178:181], v[112:113], off offset:768
	v_mfma_f32_16x16x32_bf16 v[80:83], v[166:169], v[226:229], v[80:83]
	global_load_dwordx4 v[166:169], v[126:127], off offset:912
	v_mfma_f32_16x16x32_bf16 v[68:71], v[186:189], v[226:229], v[68:71]
	global_load_dwordx4 v[186:189], v[124:125], off offset:784
	global_load_dwordx4 v[226:229], v[120:121], off offset:912
	s_waitcnt vmcnt(14)
	v_mfma_f32_16x16x32_bf16 v[28:31], v[162:165], v[230:233], v[28:31]
	s_waitcnt vmcnt(14)
	v_mfma_f32_16x16x32_bf16 v[52:55], v[234:237], v[230:233], v[52:55]
	s_waitcnt vmcnt(14)
	v_mfma_f32_16x16x32_bf16 v[56:59], v[222:225], v[230:233], v[56:59]
	s_waitcnt vmcnt(14)
	v_mfma_f32_16x16x32_bf16 v[60:63], v[246:249], v[230:233], v[60:63]
	global_load_dwordx4 v[230:233], v[118:119], off offset:912
	s_waitcnt vmcnt(14)
	v_mfma_f32_16x16x32_bf16 v[64:67], v[162:165], v[182:185], v[64:67]
	v_mfma_f32_16x16x32_bf16 v[44:47], v[234:237], v[182:185], v[44:47]
	v_mfma_f32_16x16x32_bf16 v[36:39], v[222:225], v[182:185], v[36:39]
	v_mfma_f32_16x16x32_bf16 v[24:27], v[246:249], v[182:185], v[24:27]
	global_load_dwordx4 v[182:185], v[122:123], off offset:784
	s_waitcnt vmcnt(14)
	v_mfma_f32_16x16x32_bf16 v[48:51], v[162:165], v[158:161], v[48:51]
	v_mfma_f32_16x16x32_bf16 v[40:43], v[234:237], v[158:161], v[40:43]
	v_mfma_f32_16x16x32_bf16 v[32:35], v[222:225], v[158:161], v[32:35]
	v_mfma_f32_16x16x32_bf16 v[20:23], v[246:249], v[158:161], v[20:23]
	global_load_dwordx4 v[158:161], v[114:115], off offset:784
	s_waitcnt vmcnt(14)
	v_mfma_f32_16x16x32_bf16 v[76:79], v[162:165], v[146:149], v[76:79]
	global_load_dwordx4 v[162:165], v[116:117], off offset:784
	v_mfma_f32_16x16x32_bf16 v[72:75], v[234:237], v[146:149], v[72:75]
	global_load_dwordx4 v[234:237], v[112:113], off offset:784
	v_mfma_f32_16x16x32_bf16 v[80:83], v[222:225], v[146:149], v[80:83]
	v_mfma_f32_16x16x32_bf16 v[68:71], v[246:249], v[146:149], v[68:71]
	s_waitcnt vmcnt(11)
	v_mfma_f32_16x16x32_bf16 v[28:31], v[218:221], v[150:153], v[28:31]
	s_waitcnt vmcnt(11)
	v_mfma_f32_16x16x32_bf16 v[52:55], v[154:157], v[150:153], v[52:55]
	s_waitcnt vmcnt(11)
	v_mfma_f32_16x16x32_bf16 v[56:59], v[170:173], v[150:153], v[56:59]
	s_waitcnt vmcnt(11)
	v_mfma_f32_16x16x32_bf16 v[60:63], v[174:177], v[150:153], v[60:63]
	s_waitcnt vmcnt(10)
	v_mfma_f32_16x16x32_bf16 v[64:67], v[218:221], v[238:241], v[64:67]
	v_mfma_f32_16x16x32_bf16 v[44:47], v[154:157], v[238:241], v[44:47]
	v_mfma_f32_16x16x32_bf16 v[36:39], v[170:173], v[238:241], v[36:39]
	v_mfma_f32_16x16x32_bf16 v[24:27], v[174:177], v[238:241], v[24:27]
	s_waitcnt vmcnt(9)
	v_mfma_f32_16x16x32_bf16 v[48:51], v[218:221], v[198:201], v[48:51]
	v_mfma_f32_16x16x32_bf16 v[40:43], v[154:157], v[198:201], v[40:43]
	v_mfma_f32_16x16x32_bf16 v[32:35], v[170:173], v[198:201], v[32:35]
	v_mfma_f32_16x16x32_bf16 v[20:23], v[174:177], v[198:201], v[20:23]
	s_waitcnt vmcnt(8)
	v_mfma_f32_16x16x32_bf16 v[76:79], v[218:221], v[178:181], v[76:79]
	v_mfma_f32_16x16x32_bf16 v[72:75], v[154:157], v[178:181], v[72:75]
	v_mfma_f32_16x16x32_bf16 v[80:83], v[170:173], v[178:181], v[80:83]
	v_mfma_f32_16x16x32_bf16 v[68:71], v[174:177], v[178:181], v[68:71]
	s_waitcnt vmcnt(3)
	v_mfma_f32_16x16x32_bf16 v[28:31], v[166:169], v[182:185], v[28:31]
	s_waitcnt vmcnt(3)
	v_mfma_f32_16x16x32_bf16 v[52:55], v[186:189], v[182:185], v[52:55]
	s_waitcnt vmcnt(3)
	v_mfma_f32_16x16x32_bf16 v[56:59], v[226:229], v[182:185], v[56:59]
	s_waitcnt vmcnt(3)
	v_mfma_f32_16x16x32_bf16 v[60:63], v[230:233], v[182:185], v[60:63]
	s_waitcnt vmcnt(2)
	v_mfma_f32_16x16x32_bf16 v[64:67], v[166:169], v[158:161], v[64:67]
	v_mfma_f32_16x16x32_bf16 v[44:47], v[186:189], v[158:161], v[44:47]
	v_mfma_f32_16x16x32_bf16 v[36:39], v[226:229], v[158:161], v[36:39]
	v_mfma_f32_16x16x32_bf16 v[24:27], v[230:233], v[158:161], v[24:27]
	s_waitcnt vmcnt(1)
	v_mfma_f32_16x16x32_bf16 v[48:51], v[166:169], v[162:165], v[48:51]
	v_mfma_f32_16x16x32_bf16 v[40:43], v[186:189], v[162:165], v[40:43]
	v_mfma_f32_16x16x32_bf16 v[32:35], v[226:229], v[162:165], v[32:35]
	v_mfma_f32_16x16x32_bf16 v[20:23], v[230:233], v[162:165], v[20:23]
	s_waitcnt vmcnt(0)
	v_mfma_f32_16x16x32_bf16 v[76:79], v[166:169], v[234:237], v[76:79]
	v_mfma_f32_16x16x32_bf16 v[72:75], v[186:189], v[234:237], v[72:75]
	v_mfma_f32_16x16x32_bf16 v[80:83], v[226:229], v[234:237], v[80:83]
	v_mfma_f32_16x16x32_bf16 v[68:71], v[230:233], v[234:237], v[68:71]
	s_branch .LBB0_1256
